# FIN phase loop hand-pipelined: 5 sub-iterations per trip with all loads issued up front on SGPR bases, DPP 16-lane sum, same IEEE divides
# baseline (speedup 1.0000x reference)
; DI float bflo(unsigned v) { return __uint_as_float(v << 16); }
; DI float bfhi(unsigned v) { return __uint_as_float(v & 0xffff0000u); }
; DI int opaque_tid(const VBC& vc) { int t = ((vc.wid & 3) << 6) | lane_id(); asm volatile("" : "+v"(t)); return t; }
; DI void phase_fin(const Params& p, int layer, const VBC& vc) {
;     const int ntok = layer < DEPTH - 1 ? NTOK : NLAT;
;     const u16* P = (const u16*)(p.ws + OFF_P);
;     const u16* HF = (const u16*)(p.ws + OFF_HD); const u16* HB = HF + (size_t)NTOK * 384;
;     u16* Y = (u16*)(p.ws + OFF_HY);
;     const float* gn = p.mng + layer * 384;
;     const int tid = opaque_tid(vc);
;     for (long idx = (long)VBID * 256 + tid; idx < (long)ntok * 96; idx += (long)VGRID * 256) {
;         const int tok = (int)(idx / 96), rem = (int)(idx % 96), hd = rem >> 4, q = rem & 15, col = hd * 64 + q * 4;
;         uint2 a = *(const uint2*)(HF + (size_t)tok * 384 + col), bq = *(const uint2*)(HB + (size_t)tok * 384 + col);
;         float s0 = bflo(a.x) + bflo(bq.x), s1 = bfhi(a.x) + bfhi(bq.x), s2 = bflo(a.y) + bflo(bq.y), s3 = bfhi(a.y) + bfhi(bq.y);
;         float ss = s0 * s0 + s1 * s1 + s2 * s2 + s3 * s3;
;         ss += __shfl_xor(ss, 1); ss += __shfl_xor(ss, 2); ss += __shfl_xor(ss, 4); ss += __shfl_xor(ss, 8);
;         const float rs = rsqrtf(ss * (1.f / 64.f) + LN_EPS);
;         float4 gv = *(const float4*)(gn + col);
;         uint2 o = *(const uint2*)(P + (size_t)tok * PC + P_OM + col), z = *(const uint2*)(P + (size_t)tok * PC + P_ZM + col);
.LBB0_1120:
	s_andn2_b64 vcc, exec, s[0:1]
	s_cbranch_vccnz .LBB0_1180
	v_readlane_b32 s0, v251, 60
	v_readlane_b32 s1, v251, 61
	s_cmp_eq_u32 s0, 3
	v_readlane_b32 s0, v252, 21
	v_mbcnt_lo_u32_b32 v0, -1, 0
	v_mbcnt_hi_u32_b32 v0, -1, v0
	s_nop 1
	v_or_b32_e32 v2, s0, v0
	v_readlane_b32 s0, v252, 22
	v_readlane_b32 s1, v252, 23
	v_ashrrev_i32_e32 v3, 31, v2
	s_nop 0
	v_lshl_add_u64 v[2:3], s[0:1], 0, v[2:3]
	s_mov_b32 s0, 0x300000
	s_cselect_b32 s0, s0, 0x330000
	s_mov_b32 s1, s53
	v_cmp_gt_i64_e32 vcc, s[0:1], v[2:3]
	s_and_saveexec_b64 s[2:3], vcc
	s_waitcnt lgkmcnt(0)
	s_movk_i32 s24, 0x300
	s_mov_b32 s25, 0x800000
	s_waitcnt lgkmcnt(0)
	s_mov_b32 s26, 0xaaaaaaab
	s_mov_b32 s27, 0x2aaaaaaa
	s_cbranch_execz .LBB0_1124
	v_and_b32_e32 v4, 64, v237
	v_xor_b32_e32 v0, 1, v237
	v_add_u32_e32 v4, 64, v4
	v_cmp_lt_i32_e32 vcc, v0, v4
	v_readlane_b32 s6, v252, 40
	v_readlane_b32 s7, v252, 41
	v_cndmask_b32_e32 v0, v237, v0, vcc
	v_lshlrev_b32_e32 v5, 2, v0
	v_xor_b32_e32 v0, 2, v237
	v_readlane_b32 s4, v251, 60
	v_readlane_b32 s8, v252, 3
	v_cmp_lt_i32_e32 vcc, v0, v4
	s_load_dword s6, s[6:7], 0x0
	v_readlane_b32 s5, v251, 61
	v_readlane_b32 s9, v252, 4
	v_readlane_b32 s10, v252, 5
	v_readlane_b32 s11, v252, 6
	v_readlane_b32 s12, v252, 7
	v_readlane_b32 s13, v252, 8
	v_cndmask_b32_e32 v0, v237, v0, vcc
	s_mulk_i32 s4, 0x180
	s_mov_b32 s5, s53
	v_readlane_b32 s14, v252, 9
	v_readlane_b32 s15, v252, 10
	v_readlane_b32 s16, v252, 11
	v_readlane_b32 s17, v252, 12
	s_mov_b64 s[8:9], s[12:13]
	v_lshlrev_b32_e32 v6, 2, v0
	v_xor_b32_e32 v0, 4, v237
	s_lshl_b64 s[4:5], s[4:5], 2
	s_mov_b64 s[10:11], s[14:15]
	s_mov_b64 s[12:13], s[16:17]
	v_cmp_lt_i32_e32 vcc, v0, v4
	s_add_u32 s4, s12, s4
	s_addc_u32 s5, s13, s5
	v_cndmask_b32_e32 v0, v237, v0, vcc
	v_lshlrev_b32_e32 v7, 2, v0
	v_xor_b32_e32 v0, 8, v237
	s_waitcnt lgkmcnt(0)
	s_lshl_b32 s6, s6, 1
	v_cmp_lt_i32_e32 vcc, v0, v4
	s_ashr_i32 s7, s6, 31
	v_readlane_b32 s16, v251, 33
	v_readlane_b32 s14, v251, 12
	v_cndmask_b32_e32 v0, v237, v0, vcc
	s_lshl_b64 s[6:7], s[6:7], 8
	v_readlane_b32 s17, v251, 34
	v_readlane_b32 s15, v251, 13
	v_lshlrev_b32_e32 v8, 2, v0
	v_lshlrev_b32_e32 v4, 2, v2
	s_lshl_b32 s10, s6, 2
	s_mov_b64 s[8:9], 0
	v_readlane_b32 s18, v252, 13
	v_readlane_b32 s19, v252, 14
	v_readlane_b32 s20, v252, 15
	v_readlane_b32 s21, v252, 16
	v_readlane_b32 s22, v252, 17
	v_readlane_b32 s23, v252, 18
	s_add_i32 s11, s0, -1
	s_mul_i32 s9, s6, 5
.Lfin_top:
	v_mov_b32_e32 v73, v2
	v_min_u32_e32 v20, s11, v73
	v_mul_hi_u32 v21, v20, s26
	v_lshrrev_b32_e32 v21, 6, v21
	v_mul_u32_u24_e32 v22, 0x60, v21
	v_sub_u32_e32 v22, v20, v22
	v_lshlrev_b32_e32 v23, 3, v22
	v_mul_u32_u24_e32 v24, 0x300, v21
	v_add_u32_e32 v24, v24, v23
	v_mul_lo_u32 v25, v21, s67
	v_add3_u32 v25, v25, v23, s61
	v_lshlrev_b32_e32 v26, 4, v22
	v_lshlrev_b32_e32 v27, 11, v21
	v_add_u32_e32 v27, 0x2a6f000, v27
	v_add_u32_e32 v72, v27, v23
	global_load_dwordx2 v[60:61], v24, s[14:15]
	global_load_dwordx2 v[62:63], v24, s[16:17]
	global_load_dwordx2 v[64:65], v25, s[36:37] offset:1024
	global_load_dwordx2 v[66:67], v25, s[36:37] offset:1792
	global_load_dwordx4 v[68:71], v26, s[4:5]
	v_add_u32_e32 v89, s6, v2
	v_min_u32_e32 v20, s11, v89
	v_mul_hi_u32 v21, v20, s26
	v_lshrrev_b32_e32 v21, 6, v21
	v_mul_u32_u24_e32 v22, 0x60, v21
	v_sub_u32_e32 v22, v20, v22
	v_lshlrev_b32_e32 v23, 3, v22
	v_mul_u32_u24_e32 v24, 0x300, v21
	v_add_u32_e32 v24, v24, v23
	v_mul_lo_u32 v25, v21, s67
	v_add3_u32 v25, v25, v23, s61
	v_lshlrev_b32_e32 v26, 4, v22
	v_lshlrev_b32_e32 v27, 11, v21
	v_add_u32_e32 v27, 0x2a6f000, v27
	v_add_u32_e32 v88, v27, v23
	global_load_dwordx2 v[76:77], v24, s[14:15]
	global_load_dwordx2 v[78:79], v24, s[16:17]
	global_load_dwordx2 v[80:81], v25, s[36:37] offset:1024
	global_load_dwordx2 v[82:83], v25, s[36:37] offset:1792
	global_load_dwordx4 v[84:87], v26, s[4:5]
	s_mul_i32 s8, s6, 2
	v_add_u32_e32 v105, s8, v2
	v_min_u32_e32 v20, s11, v105
	v_mul_hi_u32 v21, v20, s26
	v_lshrrev_b32_e32 v21, 6, v21
	v_mul_u32_u24_e32 v22, 0x60, v21
	v_sub_u32_e32 v22, v20, v22
	v_lshlrev_b32_e32 v23, 3, v22
	v_mul_u32_u24_e32 v24, 0x300, v21
	v_add_u32_e32 v24, v24, v23
	v_mul_lo_u32 v25, v21, s67
	v_add3_u32 v25, v25, v23, s61
	v_lshlrev_b32_e32 v26, 4, v22
	v_lshlrev_b32_e32 v27, 11, v21
	v_add_u32_e32 v27, 0x2a6f000, v27
	v_add_u32_e32 v104, v27, v23
	global_load_dwordx2 v[92:93], v24, s[14:15]
	global_load_dwordx2 v[94:95], v24, s[16:17]
	global_load_dwordx2 v[96:97], v25, s[36:37] offset:1024
	global_load_dwordx2 v[98:99], v25, s[36:37] offset:1792
	global_load_dwordx4 v[100:103], v26, s[4:5]
	s_mul_i32 s8, s6, 3
	v_add_u32_e32 v121, s8, v2
	v_min_u32_e32 v20, s11, v121
	v_mul_hi_u32 v21, v20, s26
	v_lshrrev_b32_e32 v21, 6, v21
	v_mul_u32_u24_e32 v22, 0x60, v21
	v_sub_u32_e32 v22, v20, v22
	v_lshlrev_b32_e32 v23, 3, v22
	v_mul_u32_u24_e32 v24, 0x300, v21
	v_add_u32_e32 v24, v24, v23
	v_mul_lo_u32 v25, v21, s67
	v_add3_u32 v25, v25, v23, s61
	v_lshlrev_b32_e32 v26, 4, v22
	v_lshlrev_b32_e32 v27, 11, v21
	v_add_u32_e32 v27, 0x2a6f000, v27
	v_add_u32_e32 v120, v27, v23
	global_load_dwordx2 v[108:109], v24, s[14:15]
	global_load_dwordx2 v[110:111], v24, s[16:17]
	global_load_dwordx2 v[112:113], v25, s[36:37] offset:1024
	global_load_dwordx2 v[114:115], v25, s[36:37] offset:1792
	global_load_dwordx4 v[116:119], v26, s[4:5]
	s_mul_i32 s8, s6, 4
	v_add_u32_e32 v137, s8, v2
	v_min_u32_e32 v20, s11, v137
	v_mul_hi_u32 v21, v20, s26
	v_lshrrev_b32_e32 v21, 6, v21
	v_mul_u32_u24_e32 v22, 0x60, v21
	v_sub_u32_e32 v22, v20, v22
	v_lshlrev_b32_e32 v23, 3, v22
	v_mul_u32_u24_e32 v24, 0x300, v21
	v_add_u32_e32 v24, v24, v23
	v_mul_lo_u32 v25, v21, s67
	v_add3_u32 v25, v25, v23, s61
	v_lshlrev_b32_e32 v26, 4, v22
	v_lshlrev_b32_e32 v27, 11, v21
	v_add_u32_e32 v27, 0x2a6f000, v27
	v_add_u32_e32 v136, v27, v23
	global_load_dwordx2 v[124:125], v24, s[14:15]
	global_load_dwordx2 v[126:127], v24, s[16:17]
	global_load_dwordx2 v[128:129], v25, s[36:37] offset:1024
	global_load_dwordx2 v[130:131], v25, s[36:37] offset:1792
	global_load_dwordx4 v[132:135], v26, s[4:5]
	v_cmp_gt_u32_e32 vcc, s0, v73
	s_cbranch_vccz .Lfin_skip0
; DI float bflo(unsigned v) { return __uint_as_float(v << 16); }
; DI float bfhi(unsigned v) { return __uint_as_float(v & 0xffff0000u); }
; DI float silu_f(float v) { return v / (1.f + __expf(-v)); }
; DI float sigmoid_f(float v) { return 1.f / (1.f + __expf(-v)); }
; DI void st_bf4(u16* dst, float a, float b, float c, float d) { uint2 u = {pk2(a, b), pk2(c, d)}; *(uint2*)dst = u; }
; DI void phase_fin(const Params& p, int layer, const VBC& vc) {
;     ...
;     for (long idx = (long)VBID * 256 + tid; idx < (long)ntok * 96; idx += (long)VGRID * 256) {
;         const int tok = (int)(idx / 96), rem = (int)(idx % 96), hd = rem >> 4, q = rem & 15, col = hd * 64 + q * 4;
;         uint2 a = *(const uint2*)(HF + (size_t)tok * 384 + col), bq = *(const uint2*)(HB + (size_t)tok * 384 + col);
;         float s0 = bflo(a.x) + bflo(bq.x), s1 = bfhi(a.x) + bfhi(bq.x), s2 = bflo(a.y) + bflo(bq.y), s3 = bfhi(a.y) + bfhi(bq.y);
;         float ss = s0 * s0 + s1 * s1 + s2 * s2 + s3 * s3;
;         ss += __shfl_xor(ss, 1); ss += __shfl_xor(ss, 2); ss += __shfl_xor(ss, 4); ss += __shfl_xor(ss, 8);
;         const float rs = rsqrtf(ss * (1.f / 64.f) + LN_EPS);
;         float4 gv = *(const float4*)(gn + col);
;         uint2 o = *(const uint2*)(P + (size_t)tok * PC + P_OM + col), z = *(const uint2*)(P + (size_t)tok * PC + P_ZM + col);
;         st_bf4(Y + (size_t)tok * LDK + 640 + col,
;                s0 * rs * gv.x * sigmoid_f(bflo(o.x)) * silu_f(bflo(z.x)), s1 * rs * gv.y * sigmoid_f(bfhi(o.x)) * silu_f(bfhi(z.x)),
;                s2 * rs * gv.z * sigmoid_f(bflo(o.y)) * silu_f(bflo(z.y)), s3 * rs * gv.w * sigmoid_f(bfhi(o.y)) * silu_f(bfhi(z.y)));
;     }
	s_waitcnt vmcnt(20)
	v_mov_b64_e32 v[14:15], v[60:61]
	v_mov_b64_e32 v[18:19], v[62:63]
	v_mov_b64_e32 v[26:27], v[64:65]
	v_mov_b64_e32 v[24:25], v[66:67]
	v_lshlrev_b32_e32 v20, 16, v14
	v_and_b32_e32 v21, 0xffff0000, v14
	v_lshlrev_b32_e32 v0, 16, v26
	v_and_b32_e32 v9, 0xffff0000, v26
	v_mul_f32_e32 v0, 0xbfb8aa3b, v0
	v_mul_f32_e32 v9, 0xbfb8aa3b, v9
	v_exp_f32_e32 v28, v0
	v_exp_f32_e32 v29, v9
	v_lshlrev_b32_e32 v30, 16, v25
	v_and_b32_e32 v31, 0xffff0000, v25
	v_lshlrev_b32_e32 v10, 16, v27
	v_pk_add_f32 v[28:29], v[28:29], 1.0 op_sel_hi:[1,0]
	v_mul_f32_e32 v10, 0xbfb8aa3b, v10
	v_div_scale_f32 v25, s[12:13], v29, v29, 1.0
	v_rcp_f32_e32 v32, v25
	v_exp_f32_e32 v26, v10
	v_and_b32_e32 v10, 0xffff0000, v27
	v_mul_f32_e32 v10, 0xbfb8aa3b, v10
	v_fma_f32 v33, -v25, v32, 1.0
	v_fmac_f32_e32 v32, v33, v32
	v_div_scale_f32 v33, vcc, 1.0, v29, 1.0
	v_mul_f32_e32 v34, v33, v32
	v_fma_f32 v35, -v25, v34, v33
	v_fmac_f32_e32 v34, v35, v32
	v_fma_f32 v25, -v25, v34, v33
	v_exp_f32_e32 v27, v10
	v_div_fmas_f32 v25, v25, v32, v34
	v_div_fixup_f32 v29, v25, v29, 1.0
	v_div_scale_f32 v25, s[12:13], v28, v28, 1.0
	v_rcp_f32_e32 v32, v25
	v_lshlrev_b32_e32 v0, 16, v24
	v_and_b32_e32 v9, 0xffff0000, v24
	v_mul_f32_e32 v24, 0xbfb8aa3b, v0
	v_fma_f32 v33, -v25, v32, 1.0
	v_fmac_f32_e32 v32, v33, v32
	v_div_scale_f32 v33, vcc, 1.0, v28, 1.0
	v_mul_f32_e32 v34, v33, v32
	v_fma_f32 v35, -v25, v34, v33
	v_fmac_f32_e32 v34, v35, v32
	v_fma_f32 v25, -v25, v34, v33
	v_div_fmas_f32 v25, v25, v32, v34
	v_div_fixup_f32 v28, v25, v28, 1.0
	v_mul_f32_e32 v25, 0xbfb8aa3b, v9
	v_exp_f32_e32 v24, v24
	v_exp_f32_e32 v25, v25
	v_lshlrev_b32_e32 v22, 16, v18
	v_and_b32_e32 v23, 0xffff0000, v18
	v_lshlrev_b32_e32 v14, 16, v15
	v_pk_add_f32 v[24:25], v[24:25], 1.0 op_sel_hi:[1,0]
	v_lshlrev_b32_e32 v18, 16, v19
	v_div_scale_f32 v32, s[12:13], v25, v25, v9
	v_rcp_f32_e32 v33, v32
	v_and_b32_e32 v15, 0xffff0000, v15
	v_and_b32_e32 v19, 0xffff0000, v19
	v_pk_add_f32 v[20:21], v[20:21], v[22:23]
	v_fma_f32 v34, -v32, v33, 1.0
	v_fmac_f32_e32 v33, v34, v33
	v_div_scale_f32 v34, vcc, v9, v25, v9
	v_mul_f32_e32 v35, v34, v33
	v_fma_f32 v36, -v32, v35, v34
	v_fmac_f32_e32 v35, v36, v33
	v_fma_f32 v32, -v32, v35, v34
	v_div_fmas_f32 v32, v32, v33, v35
	v_div_fixup_f32 v25, v32, v25, v9
	v_div_scale_f32 v9, s[12:13], v24, v24, v0
	v_rcp_f32_e32 v32, v9
	v_pk_add_f32 v[14:15], v[14:15], v[18:19]
	v_pk_mul_f32 v[22:23], v[20:21], v[20:21]
	v_pk_mul_f32 v[18:19], v[14:15], v[14:15]
	v_fma_f32 v33, -v9, v32, 1.0
	v_fmac_f32_e32 v32, v33, v32
	v_div_scale_f32 v33, vcc, v0, v24, v0
	v_mul_f32_e32 v34, v33, v32
	v_fma_f32 v35, -v9, v34, v33
	v_fmac_f32_e32 v34, v35, v32
	v_fma_f32 v9, -v9, v34, v33
	v_div_fmas_f32 v9, v9, v32, v34
	v_div_fixup_f32 v24, v9, v24, v0
	v_add_f32_e32 v0, v22, v23
	v_add_f32_e32 v0, v0, v18
	v_add_f32_e32 v0, v19, v0
	s_nop 1
	v_add_f32_dpp v0, v0, v0 quad_perm:[1,0,3,2] row_mask:0xf bank_mask:0xf
	s_nop 1
	v_add_f32_dpp v0, v0, v0 quad_perm:[2,3,0,1] row_mask:0xf bank_mask:0xf
	s_nop 1
	v_add_f32_dpp v0, v0, v0 row_half_mirror row_mask:0xf bank_mask:0xf
	s_nop 1
	v_add_f32_dpp v0, v0, v0 row_mirror row_mask:0xf bank_mask:0xf
	v_fmamk_f32 v0, v0, 0x3c800000, v229
	v_cmp_gt_f32_e32 vcc, s25, v0
	v_mul_f32_e32 v9, 0x4b800000, v0
	s_nop 0
	v_cndmask_b32_e32 v0, v0, v9, vcc
	v_rsq_f32_e32 v0, v0
	s_nop 0
	v_mul_f32_e32 v9, 0x45800000, v0
	v_cndmask_b32_e32 v0, v0, v9, vcc
	v_pk_mul_f32 v[14:15], v[14:15], v[0:1] op_sel_hi:[1,0]
	v_pk_mul_f32 v[18:19], v[20:21], v[0:1] op_sel_hi:[1,0]
	v_mov_b64_e32 v[10:11], v[68:69]
	v_mov_b64_e32 v[12:13], v[70:71]
	v_pk_mul_f32 v[12:13], v[12:13], v[14:15]
	v_pk_add_f32 v[14:15], v[26:27], 1.0 op_sel_hi:[1,0]
	v_mul_f32_e32 v9, 0xbfb8aa3b, v30
	v_div_scale_f32 v0, s[12:13], v15, v15, 1.0
	v_pk_mul_f32 v[10:11], v[10:11], v[18:19]
	v_exp_f32_e32 v18, v9
	v_rcp_f32_e32 v9, v0
	v_pk_mul_f32 v[10:11], v[28:29], v[10:11]
	v_fma_f32 v19, -v0, v9, 1.0
	v_fmac_f32_e32 v9, v19, v9
	v_div_scale_f32 v19, vcc, 1.0, v15, 1.0
	v_mul_f32_e32 v20, v19, v9
	v_fma_f32 v21, -v0, v20, v19
	v_fmac_f32_e32 v20, v21, v9
	v_fma_f32 v0, -v0, v20, v19
	v_div_fmas_f32 v0, v0, v9, v20
	v_div_fixup_f32 v15, v0, v15, 1.0
	v_div_scale_f32 v0, s[12:13], v14, v14, 1.0
	v_rcp_f32_e32 v9, v0
	v_pk_mul_f32 v[10:11], v[24:25], v[10:11]
	v_fma_f32 v19, -v0, v9, 1.0
	v_fmac_f32_e32 v9, v19, v9
	v_div_scale_f32 v19, vcc, 1.0, v14, 1.0
	v_mul_f32_e32 v20, v19, v9
	v_fma_f32 v21, -v0, v20, v19
	v_fmac_f32_e32 v20, v21, v9
	v_fma_f32 v0, -v0, v20, v19
	v_div_fmas_f32 v0, v0, v9, v20
	v_div_fixup_f32 v14, v0, v14, 1.0
	v_mul_f32_e32 v0, 0xbfb8aa3b, v31
	v_exp_f32_e32 v19, v0
	v_pk_mul_f32 v[12:13], v[14:15], v[12:13]
	v_cvt_pk_bf16_f32 v10, v10, v11
	v_pk_add_f32 v[14:15], v[18:19], 1.0 op_sel_hi:[1,0]
	s_nop 0
	v_div_scale_f32 v0, s[12:13], v15, v15, v31
	v_rcp_f32_e32 v9, v0
	s_nop 0
	v_fma_f32 v18, -v0, v9, 1.0
	v_fmac_f32_e32 v9, v18, v9
	v_div_scale_f32 v18, vcc, v31, v15, v31
	v_mul_f32_e32 v19, v18, v9
	v_fma_f32 v20, -v0, v19, v18
	v_fmac_f32_e32 v19, v20, v9
	v_fma_f32 v0, -v0, v19, v18
	v_div_fmas_f32 v0, v0, v9, v19
	v_div_fixup_f32 v15, v0, v15, v31
	v_div_scale_f32 v0, s[12:13], v14, v14, v30
	v_rcp_f32_e32 v9, v0
	s_nop 0
	v_fma_f32 v18, -v0, v9, 1.0
	v_fmac_f32_e32 v9, v18, v9
	v_div_scale_f32 v18, vcc, v30, v14, v30
	v_mul_f32_e32 v19, v18, v9
	v_fma_f32 v20, -v0, v19, v18
	v_fmac_f32_e32 v19, v20, v9
	v_fma_f32 v0, -v0, v19, v18
	v_div_fmas_f32 v0, v0, v9, v19
	v_div_fixup_f32 v14, v0, v14, v30
	v_pk_mul_f32 v[12:13], v[14:15], v[12:13]
	s_nop 0
	v_cvt_pk_bf16_f32 v11, v12, v13
	s_mov_b64 s[12:13], exec
	v_cmp_gt_u32_e32 vcc, s0, v73
	s_and_b64 exec, s[12:13], vcc
	global_store_dwordx2 v72, v[10:11], s[30:31] offset:1792
	s_mov_b64 exec, s[12:13]
; DI float bflo(unsigned v) { return __uint_as_float(v << 16); }
; DI float bfhi(unsigned v) { return __uint_as_float(v & 0xffff0000u); }
; DI float silu_f(float v) { return v / (1.f + __expf(-v)); }
; DI float sigmoid_f(float v) { return 1.f / (1.f + __expf(-v)); }
; DI void st_bf4(u16* dst, float a, float b, float c, float d) { uint2 u = {pk2(a, b), pk2(c, d)}; *(uint2*)dst = u; }
; DI void phase_fin(const Params& p, int layer, const VBC& vc) {
;     ...
;     for (long idx = (long)VBID * 256 + tid; idx < (long)ntok * 96; idx += (long)VGRID * 256) {
;         const int tok = (int)(idx / 96), rem = (int)(idx % 96), hd = rem >> 4, q = rem & 15, col = hd * 64 + q * 4;
;         uint2 a = *(const uint2*)(HF + (size_t)tok * 384 + col), bq = *(const uint2*)(HB + (size_t)tok * 384 + col);
;         float s0 = bflo(a.x) + bflo(bq.x), s1 = bfhi(a.x) + bfhi(bq.x), s2 = bflo(a.y) + bflo(bq.y), s3 = bfhi(a.y) + bfhi(bq.y);
;         float ss = s0 * s0 + s1 * s1 + s2 * s2 + s3 * s3;
;         ss += __shfl_xor(ss, 1); ss += __shfl_xor(ss, 2); ss += __shfl_xor(ss, 4); ss += __shfl_xor(ss, 8);
;         const float rs = rsqrtf(ss * (1.f / 64.f) + LN_EPS);
;         float4 gv = *(const float4*)(gn + col);
;         uint2 o = *(const uint2*)(P + (size_t)tok * PC + P_OM + col), z = *(const uint2*)(P + (size_t)tok * PC + P_ZM + col);
;         st_bf4(Y + (size_t)tok * LDK + 640 + col,
;                s0 * rs * gv.x * sigmoid_f(bflo(o.x)) * silu_f(bflo(z.x)), s1 * rs * gv.y * sigmoid_f(bfhi(o.x)) * silu_f(bfhi(z.x)),
;                s2 * rs * gv.z * sigmoid_f(bflo(o.y)) * silu_f(bflo(z.y)), s3 * rs * gv.w * sigmoid_f(bfhi(o.y)) * silu_f(bfhi(z.y)));
;     }
.Lfin_skip0:
	v_cmp_gt_u32_e32 vcc, s0, v89
	s_cbranch_vccz .Lfin_skip1
	s_waitcnt vmcnt(15)
	v_mov_b64_e32 v[14:15], v[76:77]
	v_mov_b64_e32 v[18:19], v[78:79]
	v_mov_b64_e32 v[26:27], v[80:81]
	v_mov_b64_e32 v[24:25], v[82:83]
	v_lshlrev_b32_e32 v20, 16, v14
	v_and_b32_e32 v21, 0xffff0000, v14
	v_lshlrev_b32_e32 v0, 16, v26
	v_and_b32_e32 v9, 0xffff0000, v26
	v_mul_f32_e32 v0, 0xbfb8aa3b, v0
	v_mul_f32_e32 v9, 0xbfb8aa3b, v9
	v_exp_f32_e32 v28, v0
	v_exp_f32_e32 v29, v9
	v_lshlrev_b32_e32 v30, 16, v25
	v_and_b32_e32 v31, 0xffff0000, v25
	v_lshlrev_b32_e32 v10, 16, v27
	v_pk_add_f32 v[28:29], v[28:29], 1.0 op_sel_hi:[1,0]
	v_mul_f32_e32 v10, 0xbfb8aa3b, v10
	v_div_scale_f32 v25, s[12:13], v29, v29, 1.0
	v_rcp_f32_e32 v32, v25
	v_exp_f32_e32 v26, v10
	v_and_b32_e32 v10, 0xffff0000, v27
	v_mul_f32_e32 v10, 0xbfb8aa3b, v10
	v_fma_f32 v33, -v25, v32, 1.0
	v_fmac_f32_e32 v32, v33, v32
	v_div_scale_f32 v33, vcc, 1.0, v29, 1.0
	v_mul_f32_e32 v34, v33, v32
	v_fma_f32 v35, -v25, v34, v33
	v_fmac_f32_e32 v34, v35, v32
	v_fma_f32 v25, -v25, v34, v33
	v_exp_f32_e32 v27, v10
	v_div_fmas_f32 v25, v25, v32, v34
	v_div_fixup_f32 v29, v25, v29, 1.0
	v_div_scale_f32 v25, s[12:13], v28, v28, 1.0
	v_rcp_f32_e32 v32, v25
	v_lshlrev_b32_e32 v0, 16, v24
	v_and_b32_e32 v9, 0xffff0000, v24
	v_mul_f32_e32 v24, 0xbfb8aa3b, v0
	v_fma_f32 v33, -v25, v32, 1.0
	v_fmac_f32_e32 v32, v33, v32
	v_div_scale_f32 v33, vcc, 1.0, v28, 1.0
	v_mul_f32_e32 v34, v33, v32
	v_fma_f32 v35, -v25, v34, v33
	v_fmac_f32_e32 v34, v35, v32
	v_fma_f32 v25, -v25, v34, v33
	v_div_fmas_f32 v25, v25, v32, v34
	v_div_fixup_f32 v28, v25, v28, 1.0
	v_mul_f32_e32 v25, 0xbfb8aa3b, v9
	v_exp_f32_e32 v24, v24
	v_exp_f32_e32 v25, v25
	v_lshlrev_b32_e32 v22, 16, v18
	v_and_b32_e32 v23, 0xffff0000, v18
	v_lshlrev_b32_e32 v14, 16, v15
	v_pk_add_f32 v[24:25], v[24:25], 1.0 op_sel_hi:[1,0]
	v_lshlrev_b32_e32 v18, 16, v19
	v_div_scale_f32 v32, s[12:13], v25, v25, v9
	v_rcp_f32_e32 v33, v32
	v_and_b32_e32 v15, 0xffff0000, v15
	v_and_b32_e32 v19, 0xffff0000, v19
	v_pk_add_f32 v[20:21], v[20:21], v[22:23]
	v_fma_f32 v34, -v32, v33, 1.0
	v_fmac_f32_e32 v33, v34, v33
	v_div_scale_f32 v34, vcc, v9, v25, v9
	v_mul_f32_e32 v35, v34, v33
	v_fma_f32 v36, -v32, v35, v34
	v_fmac_f32_e32 v35, v36, v33
	v_fma_f32 v32, -v32, v35, v34
	v_div_fmas_f32 v32, v32, v33, v35
	v_div_fixup_f32 v25, v32, v25, v9
	v_div_scale_f32 v9, s[12:13], v24, v24, v0
	v_rcp_f32_e32 v32, v9
	v_pk_add_f32 v[14:15], v[14:15], v[18:19]
	v_pk_mul_f32 v[22:23], v[20:21], v[20:21]
	v_pk_mul_f32 v[18:19], v[14:15], v[14:15]
	v_fma_f32 v33, -v9, v32, 1.0
	v_fmac_f32_e32 v32, v33, v32
	v_div_scale_f32 v33, vcc, v0, v24, v0
	v_mul_f32_e32 v34, v33, v32
	v_fma_f32 v35, -v9, v34, v33
	v_fmac_f32_e32 v34, v35, v32
	v_fma_f32 v9, -v9, v34, v33
	v_div_fmas_f32 v9, v9, v32, v34
	v_div_fixup_f32 v24, v9, v24, v0
	v_add_f32_e32 v0, v22, v23
	v_add_f32_e32 v0, v0, v18
	v_add_f32_e32 v0, v19, v0
	s_nop 1
	v_add_f32_dpp v0, v0, v0 quad_perm:[1,0,3,2] row_mask:0xf bank_mask:0xf
	s_nop 1
	v_add_f32_dpp v0, v0, v0 quad_perm:[2,3,0,1] row_mask:0xf bank_mask:0xf
	s_nop 1
	v_add_f32_dpp v0, v0, v0 row_half_mirror row_mask:0xf bank_mask:0xf
	s_nop 1
	v_add_f32_dpp v0, v0, v0 row_mirror row_mask:0xf bank_mask:0xf
	v_fmamk_f32 v0, v0, 0x3c800000, v229
	v_cmp_gt_f32_e32 vcc, s25, v0
	v_mul_f32_e32 v9, 0x4b800000, v0
	s_nop 0
	v_cndmask_b32_e32 v0, v0, v9, vcc
	v_rsq_f32_e32 v0, v0
	s_nop 0
	v_mul_f32_e32 v9, 0x45800000, v0
	v_cndmask_b32_e32 v0, v0, v9, vcc
	v_pk_mul_f32 v[14:15], v[14:15], v[0:1] op_sel_hi:[1,0]
	v_pk_mul_f32 v[18:19], v[20:21], v[0:1] op_sel_hi:[1,0]
	v_mov_b64_e32 v[10:11], v[84:85]
	v_mov_b64_e32 v[12:13], v[86:87]
	v_pk_mul_f32 v[12:13], v[12:13], v[14:15]
	v_pk_add_f32 v[14:15], v[26:27], 1.0 op_sel_hi:[1,0]
	v_mul_f32_e32 v9, 0xbfb8aa3b, v30
	v_div_scale_f32 v0, s[12:13], v15, v15, 1.0
	v_pk_mul_f32 v[10:11], v[10:11], v[18:19]
	v_exp_f32_e32 v18, v9
	v_rcp_f32_e32 v9, v0
	v_pk_mul_f32 v[10:11], v[28:29], v[10:11]
	v_fma_f32 v19, -v0, v9, 1.0
	v_fmac_f32_e32 v9, v19, v9
	v_div_scale_f32 v19, vcc, 1.0, v15, 1.0
	v_mul_f32_e32 v20, v19, v9
	v_fma_f32 v21, -v0, v20, v19
	v_fmac_f32_e32 v20, v21, v9
	v_fma_f32 v0, -v0, v20, v19
	v_div_fmas_f32 v0, v0, v9, v20
	v_div_fixup_f32 v15, v0, v15, 1.0
	v_div_scale_f32 v0, s[12:13], v14, v14, 1.0
	v_rcp_f32_e32 v9, v0
	v_pk_mul_f32 v[10:11], v[24:25], v[10:11]
	v_fma_f32 v19, -v0, v9, 1.0
	v_fmac_f32_e32 v9, v19, v9
	v_div_scale_f32 v19, vcc, 1.0, v14, 1.0
	v_mul_f32_e32 v20, v19, v9
	v_fma_f32 v21, -v0, v20, v19
	v_fmac_f32_e32 v20, v21, v9
	v_fma_f32 v0, -v0, v20, v19
	v_div_fmas_f32 v0, v0, v9, v20
	v_div_fixup_f32 v14, v0, v14, 1.0
	v_mul_f32_e32 v0, 0xbfb8aa3b, v31
	v_exp_f32_e32 v19, v0
	v_pk_mul_f32 v[12:13], v[14:15], v[12:13]
	v_cvt_pk_bf16_f32 v10, v10, v11
	v_pk_add_f32 v[14:15], v[18:19], 1.0 op_sel_hi:[1,0]
	s_nop 0
	v_div_scale_f32 v0, s[12:13], v15, v15, v31
	v_rcp_f32_e32 v9, v0
	s_nop 0
	v_fma_f32 v18, -v0, v9, 1.0
	v_fmac_f32_e32 v9, v18, v9
	v_div_scale_f32 v18, vcc, v31, v15, v31
	v_mul_f32_e32 v19, v18, v9
	v_fma_f32 v20, -v0, v19, v18
	v_fmac_f32_e32 v19, v20, v9
	v_fma_f32 v0, -v0, v19, v18
	v_div_fmas_f32 v0, v0, v9, v19
	v_div_fixup_f32 v15, v0, v15, v31
	v_div_scale_f32 v0, s[12:13], v14, v14, v30
	v_rcp_f32_e32 v9, v0
	s_nop 0
	v_fma_f32 v18, -v0, v9, 1.0
	v_fmac_f32_e32 v9, v18, v9
	v_div_scale_f32 v18, vcc, v30, v14, v30
	v_mul_f32_e32 v19, v18, v9
	v_fma_f32 v20, -v0, v19, v18
	v_fmac_f32_e32 v19, v20, v9
	v_fma_f32 v0, -v0, v19, v18
	v_div_fmas_f32 v0, v0, v9, v19
	v_div_fixup_f32 v14, v0, v14, v30
	v_pk_mul_f32 v[12:13], v[14:15], v[12:13]
	s_nop 0
	v_cvt_pk_bf16_f32 v11, v12, v13
	s_mov_b64 s[12:13], exec
	v_cmp_gt_u32_e32 vcc, s0, v89
	s_and_b64 exec, s[12:13], vcc
	global_store_dwordx2 v88, v[10:11], s[30:31] offset:1792
	s_mov_b64 exec, s[12:13]
; DI float bflo(unsigned v) { return __uint_as_float(v << 16); }
; DI float bfhi(unsigned v) { return __uint_as_float(v & 0xffff0000u); }
; DI float silu_f(float v) { return v / (1.f + __expf(-v)); }
; DI float sigmoid_f(float v) { return 1.f / (1.f + __expf(-v)); }
; DI void st_bf4(u16* dst, float a, float b, float c, float d) { uint2 u = {pk2(a, b), pk2(c, d)}; *(uint2*)dst = u; }
; DI void phase_fin(const Params& p, int layer, const VBC& vc) {
;     ...
;     for (long idx = (long)VBID * 256 + tid; idx < (long)ntok * 96; idx += (long)VGRID * 256) {
;         const int tok = (int)(idx / 96), rem = (int)(idx % 96), hd = rem >> 4, q = rem & 15, col = hd * 64 + q * 4;
;         uint2 a = *(const uint2*)(HF + (size_t)tok * 384 + col), bq = *(const uint2*)(HB + (size_t)tok * 384 + col);
;         float s0 = bflo(a.x) + bflo(bq.x), s1 = bfhi(a.x) + bfhi(bq.x), s2 = bflo(a.y) + bflo(bq.y), s3 = bfhi(a.y) + bfhi(bq.y);
;         float ss = s0 * s0 + s1 * s1 + s2 * s2 + s3 * s3;
;         ss += __shfl_xor(ss, 1); ss += __shfl_xor(ss, 2); ss += __shfl_xor(ss, 4); ss += __shfl_xor(ss, 8);
;         const float rs = rsqrtf(ss * (1.f / 64.f) + LN_EPS);
;         float4 gv = *(const float4*)(gn + col);
;         uint2 o = *(const uint2*)(P + (size_t)tok * PC + P_OM + col), z = *(const uint2*)(P + (size_t)tok * PC + P_ZM + col);
;         st_bf4(Y + (size_t)tok * LDK + 640 + col,
;                s0 * rs * gv.x * sigmoid_f(bflo(o.x)) * silu_f(bflo(z.x)), s1 * rs * gv.y * sigmoid_f(bfhi(o.x)) * silu_f(bfhi(z.x)),
;                s2 * rs * gv.z * sigmoid_f(bflo(o.y)) * silu_f(bflo(z.y)), s3 * rs * gv.w * sigmoid_f(bfhi(o.y)) * silu_f(bfhi(z.y)));
;     }
.Lfin_skip1:
	v_cmp_gt_u32_e32 vcc, s0, v105
	s_cbranch_vccz .Lfin_skip2
	s_waitcnt vmcnt(10)
	v_mov_b64_e32 v[14:15], v[92:93]
	v_mov_b64_e32 v[18:19], v[94:95]
	v_mov_b64_e32 v[26:27], v[96:97]
	v_mov_b64_e32 v[24:25], v[98:99]
	v_lshlrev_b32_e32 v20, 16, v14
	v_and_b32_e32 v21, 0xffff0000, v14
	v_lshlrev_b32_e32 v0, 16, v26
	v_and_b32_e32 v9, 0xffff0000, v26
	v_mul_f32_e32 v0, 0xbfb8aa3b, v0
	v_mul_f32_e32 v9, 0xbfb8aa3b, v9
	v_exp_f32_e32 v28, v0
	v_exp_f32_e32 v29, v9
	v_lshlrev_b32_e32 v30, 16, v25
	v_and_b32_e32 v31, 0xffff0000, v25
	v_lshlrev_b32_e32 v10, 16, v27
	v_pk_add_f32 v[28:29], v[28:29], 1.0 op_sel_hi:[1,0]
	v_mul_f32_e32 v10, 0xbfb8aa3b, v10
	v_div_scale_f32 v25, s[12:13], v29, v29, 1.0
	v_rcp_f32_e32 v32, v25
	v_exp_f32_e32 v26, v10
	v_and_b32_e32 v10, 0xffff0000, v27
	v_mul_f32_e32 v10, 0xbfb8aa3b, v10
	v_fma_f32 v33, -v25, v32, 1.0
	v_fmac_f32_e32 v32, v33, v32
	v_div_scale_f32 v33, vcc, 1.0, v29, 1.0
	v_mul_f32_e32 v34, v33, v32
	v_fma_f32 v35, -v25, v34, v33
	v_fmac_f32_e32 v34, v35, v32
	v_fma_f32 v25, -v25, v34, v33
	v_exp_f32_e32 v27, v10
	v_div_fmas_f32 v25, v25, v32, v34
	v_div_fixup_f32 v29, v25, v29, 1.0
	v_div_scale_f32 v25, s[12:13], v28, v28, 1.0
	v_rcp_f32_e32 v32, v25
	v_lshlrev_b32_e32 v0, 16, v24
	v_and_b32_e32 v9, 0xffff0000, v24
	v_mul_f32_e32 v24, 0xbfb8aa3b, v0
	v_fma_f32 v33, -v25, v32, 1.0
	v_fmac_f32_e32 v32, v33, v32
	v_div_scale_f32 v33, vcc, 1.0, v28, 1.0
	v_mul_f32_e32 v34, v33, v32
	v_fma_f32 v35, -v25, v34, v33
	v_fmac_f32_e32 v34, v35, v32
	v_fma_f32 v25, -v25, v34, v33
	v_div_fmas_f32 v25, v25, v32, v34
	v_div_fixup_f32 v28, v25, v28, 1.0
	v_mul_f32_e32 v25, 0xbfb8aa3b, v9
	v_exp_f32_e32 v24, v24
	v_exp_f32_e32 v25, v25
	v_lshlrev_b32_e32 v22, 16, v18
	v_and_b32_e32 v23, 0xffff0000, v18
	v_lshlrev_b32_e32 v14, 16, v15
	v_pk_add_f32 v[24:25], v[24:25], 1.0 op_sel_hi:[1,0]
	v_lshlrev_b32_e32 v18, 16, v19
	v_div_scale_f32 v32, s[12:13], v25, v25, v9
	v_rcp_f32_e32 v33, v32
	v_and_b32_e32 v15, 0xffff0000, v15
	v_and_b32_e32 v19, 0xffff0000, v19
	v_pk_add_f32 v[20:21], v[20:21], v[22:23]
	v_fma_f32 v34, -v32, v33, 1.0
	v_fmac_f32_e32 v33, v34, v33
	v_div_scale_f32 v34, vcc, v9, v25, v9
	v_mul_f32_e32 v35, v34, v33
	v_fma_f32 v36, -v32, v35, v34
	v_fmac_f32_e32 v35, v36, v33
	v_fma_f32 v32, -v32, v35, v34
	v_div_fmas_f32 v32, v32, v33, v35
	v_div_fixup_f32 v25, v32, v25, v9
	v_div_scale_f32 v9, s[12:13], v24, v24, v0
	v_rcp_f32_e32 v32, v9
	v_pk_add_f32 v[14:15], v[14:15], v[18:19]
	v_pk_mul_f32 v[22:23], v[20:21], v[20:21]
	v_pk_mul_f32 v[18:19], v[14:15], v[14:15]
	v_fma_f32 v33, -v9, v32, 1.0
	v_fmac_f32_e32 v32, v33, v32
	v_div_scale_f32 v33, vcc, v0, v24, v0
	v_mul_f32_e32 v34, v33, v32
	v_fma_f32 v35, -v9, v34, v33
	v_fmac_f32_e32 v34, v35, v32
	v_fma_f32 v9, -v9, v34, v33
	v_div_fmas_f32 v9, v9, v32, v34
	v_div_fixup_f32 v24, v9, v24, v0
	v_add_f32_e32 v0, v22, v23
	v_add_f32_e32 v0, v0, v18
	v_add_f32_e32 v0, v19, v0
	s_nop 1
	v_add_f32_dpp v0, v0, v0 quad_perm:[1,0,3,2] row_mask:0xf bank_mask:0xf
	s_nop 1
	v_add_f32_dpp v0, v0, v0 quad_perm:[2,3,0,1] row_mask:0xf bank_mask:0xf
	s_nop 1
	v_add_f32_dpp v0, v0, v0 row_half_mirror row_mask:0xf bank_mask:0xf
	s_nop 1
	v_add_f32_dpp v0, v0, v0 row_mirror row_mask:0xf bank_mask:0xf
	v_fmamk_f32 v0, v0, 0x3c800000, v229
	v_cmp_gt_f32_e32 vcc, s25, v0
	v_mul_f32_e32 v9, 0x4b800000, v0
	s_nop 0
	v_cndmask_b32_e32 v0, v0, v9, vcc
	v_rsq_f32_e32 v0, v0
	s_nop 0
	v_mul_f32_e32 v9, 0x45800000, v0
	v_cndmask_b32_e32 v0, v0, v9, vcc
	v_pk_mul_f32 v[14:15], v[14:15], v[0:1] op_sel_hi:[1,0]
	v_pk_mul_f32 v[18:19], v[20:21], v[0:1] op_sel_hi:[1,0]
	v_mov_b64_e32 v[10:11], v[100:101]
	v_mov_b64_e32 v[12:13], v[102:103]
	v_pk_mul_f32 v[12:13], v[12:13], v[14:15]
	v_pk_add_f32 v[14:15], v[26:27], 1.0 op_sel_hi:[1,0]
	v_mul_f32_e32 v9, 0xbfb8aa3b, v30
	v_div_scale_f32 v0, s[12:13], v15, v15, 1.0
	v_pk_mul_f32 v[10:11], v[10:11], v[18:19]
	v_exp_f32_e32 v18, v9
	v_rcp_f32_e32 v9, v0
	v_pk_mul_f32 v[10:11], v[28:29], v[10:11]
	v_fma_f32 v19, -v0, v9, 1.0
	v_fmac_f32_e32 v9, v19, v9
	v_div_scale_f32 v19, vcc, 1.0, v15, 1.0
	v_mul_f32_e32 v20, v19, v9
	v_fma_f32 v21, -v0, v20, v19
	v_fmac_f32_e32 v20, v21, v9
	v_fma_f32 v0, -v0, v20, v19
	v_div_fmas_f32 v0, v0, v9, v20
	v_div_fixup_f32 v15, v0, v15, 1.0
	v_div_scale_f32 v0, s[12:13], v14, v14, 1.0
	v_rcp_f32_e32 v9, v0
	v_pk_mul_f32 v[10:11], v[24:25], v[10:11]
	v_fma_f32 v19, -v0, v9, 1.0
	v_fmac_f32_e32 v9, v19, v9
	v_div_scale_f32 v19, vcc, 1.0, v14, 1.0
	v_mul_f32_e32 v20, v19, v9
	v_fma_f32 v21, -v0, v20, v19
	v_fmac_f32_e32 v20, v21, v9
	v_fma_f32 v0, -v0, v20, v19
	v_div_fmas_f32 v0, v0, v9, v20
	v_div_fixup_f32 v14, v0, v14, 1.0
	v_mul_f32_e32 v0, 0xbfb8aa3b, v31
	v_exp_f32_e32 v19, v0
	v_pk_mul_f32 v[12:13], v[14:15], v[12:13]
	v_cvt_pk_bf16_f32 v10, v10, v11
	v_pk_add_f32 v[14:15], v[18:19], 1.0 op_sel_hi:[1,0]
	s_nop 0
	v_div_scale_f32 v0, s[12:13], v15, v15, v31
	v_rcp_f32_e32 v9, v0
	s_nop 0
	v_fma_f32 v18, -v0, v9, 1.0
	v_fmac_f32_e32 v9, v18, v9
	v_div_scale_f32 v18, vcc, v31, v15, v31
	v_mul_f32_e32 v19, v18, v9
	v_fma_f32 v20, -v0, v19, v18
	v_fmac_f32_e32 v19, v20, v9
	v_fma_f32 v0, -v0, v19, v18
	v_div_fmas_f32 v0, v0, v9, v19
	v_div_fixup_f32 v15, v0, v15, v31
	v_div_scale_f32 v0, s[12:13], v14, v14, v30
	v_rcp_f32_e32 v9, v0
	s_nop 0
	v_fma_f32 v18, -v0, v9, 1.0
	v_fmac_f32_e32 v9, v18, v9
	v_div_scale_f32 v18, vcc, v30, v14, v30
	v_mul_f32_e32 v19, v18, v9
	v_fma_f32 v20, -v0, v19, v18
	v_fmac_f32_e32 v19, v20, v9
	v_fma_f32 v0, -v0, v19, v18
	v_div_fmas_f32 v0, v0, v9, v19
	v_div_fixup_f32 v14, v0, v14, v30
	v_pk_mul_f32 v[12:13], v[14:15], v[12:13]
	s_nop 0
	v_cvt_pk_bf16_f32 v11, v12, v13
	s_mov_b64 s[12:13], exec
	v_cmp_gt_u32_e32 vcc, s0, v105
	s_and_b64 exec, s[12:13], vcc
	global_store_dwordx2 v104, v[10:11], s[30:31] offset:1792
	s_mov_b64 exec, s[12:13]
; DI float bflo(unsigned v) { return __uint_as_float(v << 16); }
; DI float bfhi(unsigned v) { return __uint_as_float(v & 0xffff0000u); }
; DI float silu_f(float v) { return v / (1.f + __expf(-v)); }
; DI float sigmoid_f(float v) { return 1.f / (1.f + __expf(-v)); }
; DI void st_bf4(u16* dst, float a, float b, float c, float d) { uint2 u = {pk2(a, b), pk2(c, d)}; *(uint2*)dst = u; }
; DI void phase_fin(const Params& p, int layer, const VBC& vc) {
;     ...
;     for (long idx = (long)VBID * 256 + tid; idx < (long)ntok * 96; idx += (long)VGRID * 256) {
;         const int tok = (int)(idx / 96), rem = (int)(idx % 96), hd = rem >> 4, q = rem & 15, col = hd * 64 + q * 4;
;         uint2 a = *(const uint2*)(HF + (size_t)tok * 384 + col), bq = *(const uint2*)(HB + (size_t)tok * 384 + col);
;         float s0 = bflo(a.x) + bflo(bq.x), s1 = bfhi(a.x) + bfhi(bq.x), s2 = bflo(a.y) + bflo(bq.y), s3 = bfhi(a.y) + bfhi(bq.y);
;         float ss = s0 * s0 + s1 * s1 + s2 * s2 + s3 * s3;
;         ss += __shfl_xor(ss, 1); ss += __shfl_xor(ss, 2); ss += __shfl_xor(ss, 4); ss += __shfl_xor(ss, 8);
;         const float rs = rsqrtf(ss * (1.f / 64.f) + LN_EPS);
;         float4 gv = *(const float4*)(gn + col);
;         uint2 o = *(const uint2*)(P + (size_t)tok * PC + P_OM + col), z = *(const uint2*)(P + (size_t)tok * PC + P_ZM + col);
;         st_bf4(Y + (size_t)tok * LDK + 640 + col,
;                s0 * rs * gv.x * sigmoid_f(bflo(o.x)) * silu_f(bflo(z.x)), s1 * rs * gv.y * sigmoid_f(bfhi(o.x)) * silu_f(bfhi(z.x)),
;                s2 * rs * gv.z * sigmoid_f(bflo(o.y)) * silu_f(bflo(z.y)), s3 * rs * gv.w * sigmoid_f(bfhi(o.y)) * silu_f(bfhi(z.y)));
;     }
.Lfin_skip2:
	v_cmp_gt_u32_e32 vcc, s0, v121
	s_cbranch_vccz .Lfin_skip3
	s_waitcnt vmcnt(5)
	v_mov_b64_e32 v[14:15], v[108:109]
	v_mov_b64_e32 v[18:19], v[110:111]
	v_mov_b64_e32 v[26:27], v[112:113]
	v_mov_b64_e32 v[24:25], v[114:115]
	v_lshlrev_b32_e32 v20, 16, v14
	v_and_b32_e32 v21, 0xffff0000, v14
	v_lshlrev_b32_e32 v0, 16, v26
	v_and_b32_e32 v9, 0xffff0000, v26
	v_mul_f32_e32 v0, 0xbfb8aa3b, v0
	v_mul_f32_e32 v9, 0xbfb8aa3b, v9
	v_exp_f32_e32 v28, v0
	v_exp_f32_e32 v29, v9
	v_lshlrev_b32_e32 v30, 16, v25
	v_and_b32_e32 v31, 0xffff0000, v25
	v_lshlrev_b32_e32 v10, 16, v27
	v_pk_add_f32 v[28:29], v[28:29], 1.0 op_sel_hi:[1,0]
	v_mul_f32_e32 v10, 0xbfb8aa3b, v10
	v_div_scale_f32 v25, s[12:13], v29, v29, 1.0
	v_rcp_f32_e32 v32, v25
	v_exp_f32_e32 v26, v10
	v_and_b32_e32 v10, 0xffff0000, v27
	v_mul_f32_e32 v10, 0xbfb8aa3b, v10
	v_fma_f32 v33, -v25, v32, 1.0
	v_fmac_f32_e32 v32, v33, v32
	v_div_scale_f32 v33, vcc, 1.0, v29, 1.0
	v_mul_f32_e32 v34, v33, v32
	v_fma_f32 v35, -v25, v34, v33
	v_fmac_f32_e32 v34, v35, v32
	v_fma_f32 v25, -v25, v34, v33
	v_exp_f32_e32 v27, v10
	v_div_fmas_f32 v25, v25, v32, v34
	v_div_fixup_f32 v29, v25, v29, 1.0
	v_div_scale_f32 v25, s[12:13], v28, v28, 1.0
	v_rcp_f32_e32 v32, v25
	v_lshlrev_b32_e32 v0, 16, v24
	v_and_b32_e32 v9, 0xffff0000, v24
	v_mul_f32_e32 v24, 0xbfb8aa3b, v0
	v_fma_f32 v33, -v25, v32, 1.0
	v_fmac_f32_e32 v32, v33, v32
	v_div_scale_f32 v33, vcc, 1.0, v28, 1.0
	v_mul_f32_e32 v34, v33, v32
	v_fma_f32 v35, -v25, v34, v33
	v_fmac_f32_e32 v34, v35, v32
	v_fma_f32 v25, -v25, v34, v33
	v_div_fmas_f32 v25, v25, v32, v34
	v_div_fixup_f32 v28, v25, v28, 1.0
	v_mul_f32_e32 v25, 0xbfb8aa3b, v9
	v_exp_f32_e32 v24, v24
	v_exp_f32_e32 v25, v25
	v_lshlrev_b32_e32 v22, 16, v18
	v_and_b32_e32 v23, 0xffff0000, v18
	v_lshlrev_b32_e32 v14, 16, v15
	v_pk_add_f32 v[24:25], v[24:25], 1.0 op_sel_hi:[1,0]
	v_lshlrev_b32_e32 v18, 16, v19
	v_div_scale_f32 v32, s[12:13], v25, v25, v9
	v_rcp_f32_e32 v33, v32
	v_and_b32_e32 v15, 0xffff0000, v15
	v_and_b32_e32 v19, 0xffff0000, v19
	v_pk_add_f32 v[20:21], v[20:21], v[22:23]
	v_fma_f32 v34, -v32, v33, 1.0
	v_fmac_f32_e32 v33, v34, v33
	v_div_scale_f32 v34, vcc, v9, v25, v9
	v_mul_f32_e32 v35, v34, v33
	v_fma_f32 v36, -v32, v35, v34
	v_fmac_f32_e32 v35, v36, v33
	v_fma_f32 v32, -v32, v35, v34
	v_div_fmas_f32 v32, v32, v33, v35
	v_div_fixup_f32 v25, v32, v25, v9
	v_div_scale_f32 v9, s[12:13], v24, v24, v0
	v_rcp_f32_e32 v32, v9
	v_pk_add_f32 v[14:15], v[14:15], v[18:19]
	v_pk_mul_f32 v[22:23], v[20:21], v[20:21]
	v_pk_mul_f32 v[18:19], v[14:15], v[14:15]
	v_fma_f32 v33, -v9, v32, 1.0
	v_fmac_f32_e32 v32, v33, v32
	v_div_scale_f32 v33, vcc, v0, v24, v0
	v_mul_f32_e32 v34, v33, v32
	v_fma_f32 v35, -v9, v34, v33
	v_fmac_f32_e32 v34, v35, v32
	v_fma_f32 v9, -v9, v34, v33
	v_div_fmas_f32 v9, v9, v32, v34
	v_div_fixup_f32 v24, v9, v24, v0
	v_add_f32_e32 v0, v22, v23
	v_add_f32_e32 v0, v0, v18
	v_add_f32_e32 v0, v19, v0
	s_nop 1
	v_add_f32_dpp v0, v0, v0 quad_perm:[1,0,3,2] row_mask:0xf bank_mask:0xf
	s_nop 1
	v_add_f32_dpp v0, v0, v0 quad_perm:[2,3,0,1] row_mask:0xf bank_mask:0xf
	s_nop 1
	v_add_f32_dpp v0, v0, v0 row_half_mirror row_mask:0xf bank_mask:0xf
	s_nop 1
	v_add_f32_dpp v0, v0, v0 row_mirror row_mask:0xf bank_mask:0xf
	v_fmamk_f32 v0, v0, 0x3c800000, v229
	v_cmp_gt_f32_e32 vcc, s25, v0
	v_mul_f32_e32 v9, 0x4b800000, v0
	s_nop 0
	v_cndmask_b32_e32 v0, v0, v9, vcc
	v_rsq_f32_e32 v0, v0
	s_nop 0
	v_mul_f32_e32 v9, 0x45800000, v0
	v_cndmask_b32_e32 v0, v0, v9, vcc
	v_pk_mul_f32 v[14:15], v[14:15], v[0:1] op_sel_hi:[1,0]
	v_pk_mul_f32 v[18:19], v[20:21], v[0:1] op_sel_hi:[1,0]
	v_mov_b64_e32 v[10:11], v[116:117]
	v_mov_b64_e32 v[12:13], v[118:119]
	v_pk_mul_f32 v[12:13], v[12:13], v[14:15]
	v_pk_add_f32 v[14:15], v[26:27], 1.0 op_sel_hi:[1,0]
	v_mul_f32_e32 v9, 0xbfb8aa3b, v30
	v_div_scale_f32 v0, s[12:13], v15, v15, 1.0
	v_pk_mul_f32 v[10:11], v[10:11], v[18:19]
	v_exp_f32_e32 v18, v9
	v_rcp_f32_e32 v9, v0
	v_pk_mul_f32 v[10:11], v[28:29], v[10:11]
	v_fma_f32 v19, -v0, v9, 1.0
	v_fmac_f32_e32 v9, v19, v9
	v_div_scale_f32 v19, vcc, 1.0, v15, 1.0
	v_mul_f32_e32 v20, v19, v9
	v_fma_f32 v21, -v0, v20, v19
	v_fmac_f32_e32 v20, v21, v9
	v_fma_f32 v0, -v0, v20, v19
	v_div_fmas_f32 v0, v0, v9, v20
	v_div_fixup_f32 v15, v0, v15, 1.0
	v_div_scale_f32 v0, s[12:13], v14, v14, 1.0
	v_rcp_f32_e32 v9, v0
	v_pk_mul_f32 v[10:11], v[24:25], v[10:11]
	v_fma_f32 v19, -v0, v9, 1.0
	v_fmac_f32_e32 v9, v19, v9
	v_div_scale_f32 v19, vcc, 1.0, v14, 1.0
	v_mul_f32_e32 v20, v19, v9
	v_fma_f32 v21, -v0, v20, v19
	v_fmac_f32_e32 v20, v21, v9
	v_fma_f32 v0, -v0, v20, v19
	v_div_fmas_f32 v0, v0, v9, v20
	v_div_fixup_f32 v14, v0, v14, 1.0
	v_mul_f32_e32 v0, 0xbfb8aa3b, v31
	v_exp_f32_e32 v19, v0
	v_pk_mul_f32 v[12:13], v[14:15], v[12:13]
	v_cvt_pk_bf16_f32 v10, v10, v11
	v_pk_add_f32 v[14:15], v[18:19], 1.0 op_sel_hi:[1,0]
	s_nop 0
	v_div_scale_f32 v0, s[12:13], v15, v15, v31
	v_rcp_f32_e32 v9, v0
	s_nop 0
	v_fma_f32 v18, -v0, v9, 1.0
	v_fmac_f32_e32 v9, v18, v9
	v_div_scale_f32 v18, vcc, v31, v15, v31
	v_mul_f32_e32 v19, v18, v9
	v_fma_f32 v20, -v0, v19, v18
	v_fmac_f32_e32 v19, v20, v9
	v_fma_f32 v0, -v0, v19, v18
	v_div_fmas_f32 v0, v0, v9, v19
	v_div_fixup_f32 v15, v0, v15, v31
	v_div_scale_f32 v0, s[12:13], v14, v14, v30
	v_rcp_f32_e32 v9, v0
	s_nop 0
	v_fma_f32 v18, -v0, v9, 1.0
	v_fmac_f32_e32 v9, v18, v9
	v_div_scale_f32 v18, vcc, v30, v14, v30
	v_mul_f32_e32 v19, v18, v9
	v_fma_f32 v20, -v0, v19, v18
	v_fmac_f32_e32 v19, v20, v9
	v_fma_f32 v0, -v0, v19, v18
	v_div_fmas_f32 v0, v0, v9, v19
	v_div_fixup_f32 v14, v0, v14, v30
	v_pk_mul_f32 v[12:13], v[14:15], v[12:13]
	s_nop 0
	v_cvt_pk_bf16_f32 v11, v12, v13
	s_mov_b64 s[12:13], exec
	v_cmp_gt_u32_e32 vcc, s0, v121
	s_and_b64 exec, s[12:13], vcc
	global_store_dwordx2 v120, v[10:11], s[30:31] offset:1792
	s_mov_b64 exec, s[12:13]
; DI float bflo(unsigned v) { return __uint_as_float(v << 16); }
; DI float bfhi(unsigned v) { return __uint_as_float(v & 0xffff0000u); }
; DI float silu_f(float v) { return v / (1.f + __expf(-v)); }
; DI float sigmoid_f(float v) { return 1.f / (1.f + __expf(-v)); }
; DI void st_bf4(u16* dst, float a, float b, float c, float d) { uint2 u = {pk2(a, b), pk2(c, d)}; *(uint2*)dst = u; }
; DI void phase_fin(const Params& p, int layer, const VBC& vc) {
;     ...
;     for (long idx = (long)VBID * 256 + tid; idx < (long)ntok * 96; idx += (long)VGRID * 256) {
;         const int tok = (int)(idx / 96), rem = (int)(idx % 96), hd = rem >> 4, q = rem & 15, col = hd * 64 + q * 4;
;         uint2 a = *(const uint2*)(HF + (size_t)tok * 384 + col), bq = *(const uint2*)(HB + (size_t)tok * 384 + col);
;         float s0 = bflo(a.x) + bflo(bq.x), s1 = bfhi(a.x) + bfhi(bq.x), s2 = bflo(a.y) + bflo(bq.y), s3 = bfhi(a.y) + bfhi(bq.y);
;         float ss = s0 * s0 + s1 * s1 + s2 * s2 + s3 * s3;
;         ss += __shfl_xor(ss, 1); ss += __shfl_xor(ss, 2); ss += __shfl_xor(ss, 4); ss += __shfl_xor(ss, 8);
;         const float rs = rsqrtf(ss * (1.f / 64.f) + LN_EPS);
;         float4 gv = *(const float4*)(gn + col);
;         uint2 o = *(const uint2*)(P + (size_t)tok * PC + P_OM + col), z = *(const uint2*)(P + (size_t)tok * PC + P_ZM + col);
;         st_bf4(Y + (size_t)tok * LDK + 640 + col,
;                s0 * rs * gv.x * sigmoid_f(bflo(o.x)) * silu_f(bflo(z.x)), s1 * rs * gv.y * sigmoid_f(bfhi(o.x)) * silu_f(bfhi(z.x)),
;                s2 * rs * gv.z * sigmoid_f(bflo(o.y)) * silu_f(bflo(z.y)), s3 * rs * gv.w * sigmoid_f(bfhi(o.y)) * silu_f(bfhi(z.y)));
;     }
.Lfin_skip3:
	v_cmp_gt_u32_e32 vcc, s0, v137
	s_cbranch_vccz .Lfin_skip4
	s_waitcnt vmcnt(0)
	v_mov_b64_e32 v[14:15], v[124:125]
	v_mov_b64_e32 v[18:19], v[126:127]
	v_mov_b64_e32 v[26:27], v[128:129]
	v_mov_b64_e32 v[24:25], v[130:131]
	v_lshlrev_b32_e32 v20, 16, v14
	v_and_b32_e32 v21, 0xffff0000, v14
	v_lshlrev_b32_e32 v0, 16, v26
	v_and_b32_e32 v9, 0xffff0000, v26
	v_mul_f32_e32 v0, 0xbfb8aa3b, v0
	v_mul_f32_e32 v9, 0xbfb8aa3b, v9
	v_exp_f32_e32 v28, v0
	v_exp_f32_e32 v29, v9
	v_lshlrev_b32_e32 v30, 16, v25
	v_and_b32_e32 v31, 0xffff0000, v25
	v_lshlrev_b32_e32 v10, 16, v27
	v_pk_add_f32 v[28:29], v[28:29], 1.0 op_sel_hi:[1,0]
	v_mul_f32_e32 v10, 0xbfb8aa3b, v10
	v_div_scale_f32 v25, s[12:13], v29, v29, 1.0
	v_rcp_f32_e32 v32, v25
	v_exp_f32_e32 v26, v10
	v_and_b32_e32 v10, 0xffff0000, v27
	v_mul_f32_e32 v10, 0xbfb8aa3b, v10
	v_fma_f32 v33, -v25, v32, 1.0
	v_fmac_f32_e32 v32, v33, v32
	v_div_scale_f32 v33, vcc, 1.0, v29, 1.0
	v_mul_f32_e32 v34, v33, v32
	v_fma_f32 v35, -v25, v34, v33
	v_fmac_f32_e32 v34, v35, v32
	v_fma_f32 v25, -v25, v34, v33
	v_exp_f32_e32 v27, v10
	v_div_fmas_f32 v25, v25, v32, v34
	v_div_fixup_f32 v29, v25, v29, 1.0
	v_div_scale_f32 v25, s[12:13], v28, v28, 1.0
	v_rcp_f32_e32 v32, v25
	v_lshlrev_b32_e32 v0, 16, v24
	v_and_b32_e32 v9, 0xffff0000, v24
	v_mul_f32_e32 v24, 0xbfb8aa3b, v0
	v_fma_f32 v33, -v25, v32, 1.0
	v_fmac_f32_e32 v32, v33, v32
	v_div_scale_f32 v33, vcc, 1.0, v28, 1.0
	v_mul_f32_e32 v34, v33, v32
	v_fma_f32 v35, -v25, v34, v33
	v_fmac_f32_e32 v34, v35, v32
	v_fma_f32 v25, -v25, v34, v33
	v_div_fmas_f32 v25, v25, v32, v34
	v_div_fixup_f32 v28, v25, v28, 1.0
	v_mul_f32_e32 v25, 0xbfb8aa3b, v9
	v_exp_f32_e32 v24, v24
	v_exp_f32_e32 v25, v25
	v_lshlrev_b32_e32 v22, 16, v18
	v_and_b32_e32 v23, 0xffff0000, v18
	v_lshlrev_b32_e32 v14, 16, v15
	v_pk_add_f32 v[24:25], v[24:25], 1.0 op_sel_hi:[1,0]
	v_lshlrev_b32_e32 v18, 16, v19
	v_div_scale_f32 v32, s[12:13], v25, v25, v9
	v_rcp_f32_e32 v33, v32
	v_and_b32_e32 v15, 0xffff0000, v15
	v_and_b32_e32 v19, 0xffff0000, v19
	v_pk_add_f32 v[20:21], v[20:21], v[22:23]
	v_fma_f32 v34, -v32, v33, 1.0
	v_fmac_f32_e32 v33, v34, v33
	v_div_scale_f32 v34, vcc, v9, v25, v9
	v_mul_f32_e32 v35, v34, v33
	v_fma_f32 v36, -v32, v35, v34
	v_fmac_f32_e32 v35, v36, v33
	v_fma_f32 v32, -v32, v35, v34
	v_div_fmas_f32 v32, v32, v33, v35
	v_div_fixup_f32 v25, v32, v25, v9
	v_div_scale_f32 v9, s[12:13], v24, v24, v0
	v_rcp_f32_e32 v32, v9
	v_pk_add_f32 v[14:15], v[14:15], v[18:19]
	v_pk_mul_f32 v[22:23], v[20:21], v[20:21]
	v_pk_mul_f32 v[18:19], v[14:15], v[14:15]
	v_fma_f32 v33, -v9, v32, 1.0
	v_fmac_f32_e32 v32, v33, v32
	v_div_scale_f32 v33, vcc, v0, v24, v0
	v_mul_f32_e32 v34, v33, v32
	v_fma_f32 v35, -v9, v34, v33
	v_fmac_f32_e32 v34, v35, v32
	v_fma_f32 v9, -v9, v34, v33
	v_div_fmas_f32 v9, v9, v32, v34
	v_div_fixup_f32 v24, v9, v24, v0
	v_add_f32_e32 v0, v22, v23
	v_add_f32_e32 v0, v0, v18
	v_add_f32_e32 v0, v19, v0
	s_nop 1
	v_add_f32_dpp v0, v0, v0 quad_perm:[1,0,3,2] row_mask:0xf bank_mask:0xf
	s_nop 1
	v_add_f32_dpp v0, v0, v0 quad_perm:[2,3,0,1] row_mask:0xf bank_mask:0xf
	s_nop 1
	v_add_f32_dpp v0, v0, v0 row_half_mirror row_mask:0xf bank_mask:0xf
	s_nop 1
	v_add_f32_dpp v0, v0, v0 row_mirror row_mask:0xf bank_mask:0xf
	v_fmamk_f32 v0, v0, 0x3c800000, v229
	v_cmp_gt_f32_e32 vcc, s25, v0
	v_mul_f32_e32 v9, 0x4b800000, v0
	s_nop 0
	v_cndmask_b32_e32 v0, v0, v9, vcc
	v_rsq_f32_e32 v0, v0
	s_nop 0
	v_mul_f32_e32 v9, 0x45800000, v0
	v_cndmask_b32_e32 v0, v0, v9, vcc
	v_pk_mul_f32 v[14:15], v[14:15], v[0:1] op_sel_hi:[1,0]
	v_pk_mul_f32 v[18:19], v[20:21], v[0:1] op_sel_hi:[1,0]
	v_mov_b64_e32 v[10:11], v[132:133]
	v_mov_b64_e32 v[12:13], v[134:135]
	v_pk_mul_f32 v[12:13], v[12:13], v[14:15]
	v_pk_add_f32 v[14:15], v[26:27], 1.0 op_sel_hi:[1,0]
	v_mul_f32_e32 v9, 0xbfb8aa3b, v30
	v_div_scale_f32 v0, s[12:13], v15, v15, 1.0
	v_pk_mul_f32 v[10:11], v[10:11], v[18:19]
	v_exp_f32_e32 v18, v9
	v_rcp_f32_e32 v9, v0
	v_pk_mul_f32 v[10:11], v[28:29], v[10:11]
	v_fma_f32 v19, -v0, v9, 1.0
	v_fmac_f32_e32 v9, v19, v9
	v_div_scale_f32 v19, vcc, 1.0, v15, 1.0
	v_mul_f32_e32 v20, v19, v9
	v_fma_f32 v21, -v0, v20, v19
	v_fmac_f32_e32 v20, v21, v9
	v_fma_f32 v0, -v0, v20, v19
	v_div_fmas_f32 v0, v0, v9, v20
	v_div_fixup_f32 v15, v0, v15, 1.0
	v_div_scale_f32 v0, s[12:13], v14, v14, 1.0
	v_rcp_f32_e32 v9, v0
	v_pk_mul_f32 v[10:11], v[24:25], v[10:11]
	v_fma_f32 v19, -v0, v9, 1.0
	v_fmac_f32_e32 v9, v19, v9
	v_div_scale_f32 v19, vcc, 1.0, v14, 1.0
	v_mul_f32_e32 v20, v19, v9
	v_fma_f32 v21, -v0, v20, v19
	v_fmac_f32_e32 v20, v21, v9
	v_fma_f32 v0, -v0, v20, v19
	v_div_fmas_f32 v0, v0, v9, v20
	v_div_fixup_f32 v14, v0, v14, 1.0
	v_mul_f32_e32 v0, 0xbfb8aa3b, v31
	v_exp_f32_e32 v19, v0
	v_pk_mul_f32 v[12:13], v[14:15], v[12:13]
	v_cvt_pk_bf16_f32 v10, v10, v11
	v_pk_add_f32 v[14:15], v[18:19], 1.0 op_sel_hi:[1,0]
	s_nop 0
	v_div_scale_f32 v0, s[12:13], v15, v15, v31
	v_rcp_f32_e32 v9, v0
	s_nop 0
	v_fma_f32 v18, -v0, v9, 1.0
	v_fmac_f32_e32 v9, v18, v9
	v_div_scale_f32 v18, vcc, v31, v15, v31
	v_mul_f32_e32 v19, v18, v9
	v_fma_f32 v20, -v0, v19, v18
	v_fmac_f32_e32 v19, v20, v9
	v_fma_f32 v0, -v0, v19, v18
	v_div_fmas_f32 v0, v0, v9, v19
	v_div_fixup_f32 v15, v0, v15, v31
	v_div_scale_f32 v0, s[12:13], v14, v14, v30
	v_rcp_f32_e32 v9, v0
	s_nop 0
	v_fma_f32 v18, -v0, v9, 1.0
	v_fmac_f32_e32 v9, v18, v9
	v_div_scale_f32 v18, vcc, v30, v14, v30
	v_mul_f32_e32 v19, v18, v9
	v_fma_f32 v20, -v0, v19, v18
	v_fmac_f32_e32 v19, v20, v9
	v_fma_f32 v0, -v0, v19, v18
	v_div_fmas_f32 v0, v0, v9, v19
	v_div_fixup_f32 v14, v0, v14, v30
	v_pk_mul_f32 v[12:13], v[14:15], v[12:13]
	s_nop 0
	v_cvt_pk_bf16_f32 v11, v12, v13
	s_mov_b64 s[12:13], exec
	v_cmp_gt_u32_e32 vcc, s0, v137
	s_and_b64 exec, s[12:13], vcc
	global_store_dwordx2 v136, v[10:11], s[30:31] offset:1792
	s_mov_b64 exec, s[12:13]
.Lfin_skip4:
	v_add_u32_e32 v2, s9, v2
	v_cmp_gt_u32_e32 vcc, s0, v2
	s_cbranch_vccnz .Lfin_top
	s_waitcnt vmcnt(0)
